# grid barrier: non-leader workgroups start an L2 write-back while they wait, so the last arriver's release finds a mostly clean L2
# baseline (speedup 1.0000x reference)
.LBB0_79:
	s_or_b64 exec, exec, s[10:11]
	v_cvt_f32_u32_e32 v4, v2
	s_waitcnt vmcnt(0)
	v_readfirstlane_b32 s3, v3
	v_sub_u32_e32 v3, 0, v2
	v_rcp_iflag_f32_e32 v4, v4
	v_add_u32_e32 v5, s3, v1
	v_mul_f32_e32 v4, 0x4f7ffffe, v4
	v_cvt_u32_f32_e32 v4, v4
	v_mul_lo_u32 v1, v3, v4
	v_mul_hi_u32 v1, v4, v1
	v_add_u32_e32 v1, v4, v1
	v_mul_hi_u32 v1, v5, v1
	v_mul_lo_u32 v3, v1, v2
	v_sub_u32_e32 v3, v5, v3
	v_add_u32_e32 v4, 1, v1
	v_cmp_ge_u32_e32 vcc, v3, v2
	s_nop 1
	v_cndmask_b32_e32 v1, v1, v4, vcc
	v_sub_u32_e32 v4, v3, v2
	v_cndmask_b32_e32 v3, v3, v4, vcc
	v_add_u32_e32 v4, 1, v1
	v_cmp_ge_u32_e32 vcc, v3, v2
	v_add_u32_e32 v3, 1, v5
	s_nop 0
	v_cndmask_b32_e32 v1, v1, v4, vcc
	v_mul_lo_u32 v4, v2, v1
	v_add_u32_e32 v2, v4, v2
	v_cmp_ne_u32_e32 vcc, v3, v2
	s_and_saveexec_b64 s[8:9], vcc
	s_xor_b64 s[8:9], exec, s[8:9]
	s_cbranch_execz .LBB0_93
	s_waitcnt lgkmcnt(0)
	buffer_wbl2 sc1
	v_mov_b32_e32 v0, 0x2000
	global_load_dword v0, v0, s[6:7] offset:1024 sc1
	s_add_u32 s34, s6, 0x2400
	s_addc_u32 s35, s7, 0
	s_waitcnt vmcnt(0)
	v_cmp_eq_u32_e32 vcc, v0, v1
	s_and_saveexec_b64 s[10:11], vcc
	s_cbranch_execz .LBB0_92
	s_add_u32 s14, s22, 0x4200
	s_addc_u32 s15, s23, 0
	s_mov_b32 s3, 1
	s_mov_b64 s[38:39], 0
	v_mov_b32_e32 v0, 0
	s_branch .LBB0_83

.LBB0_293:
	s_or_b64 exec, exec, s[10:11]
	v_cvt_f32_u32_e32 v4, v2
	s_waitcnt vmcnt(0)
	v_readfirstlane_b32 s3, v3
	v_sub_u32_e32 v3, 0, v2
	v_rcp_iflag_f32_e32 v4, v4
	v_add_u32_e32 v5, s3, v1
	v_mul_f32_e32 v4, 0x4f7ffffe, v4
	v_cvt_u32_f32_e32 v4, v4
	v_mul_lo_u32 v1, v3, v4
	v_mul_hi_u32 v1, v4, v1
	v_add_u32_e32 v1, v4, v1
	v_mul_hi_u32 v1, v5, v1
	v_mul_lo_u32 v3, v1, v2
	v_sub_u32_e32 v3, v5, v3
	v_add_u32_e32 v4, 1, v1
	v_cmp_ge_u32_e32 vcc, v3, v2
	s_nop 1
	v_cndmask_b32_e32 v1, v1, v4, vcc
	v_sub_u32_e32 v4, v3, v2
	v_cndmask_b32_e32 v3, v3, v4, vcc
	v_add_u32_e32 v4, 1, v1
	v_cmp_ge_u32_e32 vcc, v3, v2
	v_add_u32_e32 v3, 1, v5
	s_nop 0
	v_cndmask_b32_e32 v1, v1, v4, vcc
	v_mul_lo_u32 v4, v2, v1
	v_add_u32_e32 v2, v4, v2
	v_cmp_ne_u32_e32 vcc, v3, v2
	s_and_saveexec_b64 s[8:9], vcc
	s_xor_b64 s[8:9], exec, s[8:9]
	s_cbranch_execz .LBB0_307
	s_waitcnt lgkmcnt(0)
	buffer_wbl2 sc1
	v_mov_b32_e32 v0, 0x2000
	global_load_dword v0, v0, s[6:7] offset:1024 sc1
	s_add_u32 s38, s6, 0x2400
	s_addc_u32 s39, s7, 0
	s_waitcnt vmcnt(0)
	v_cmp_eq_u32_e32 vcc, v0, v1
	s_and_saveexec_b64 s[10:11], vcc
	s_cbranch_execz .LBB0_306
	s_add_u32 s14, s22, 0x4200
	s_addc_u32 s15, s23, 0
	s_mov_b32 s3, 1
	s_mov_b64 s[40:41], 0
	v_mov_b32_e32 v0, 0
	s_branch .LBB0_297

.LBB0_511:
	s_or_b64 exec, exec, s[10:11]
	v_cvt_f32_u32_e32 v4, v2
	s_waitcnt vmcnt(0)
	v_readfirstlane_b32 s3, v3
	v_sub_u32_e32 v3, 0, v2
	v_rcp_iflag_f32_e32 v4, v4
	v_add_u32_e32 v5, s3, v1
	v_mul_f32_e32 v4, 0x4f7ffffe, v4
	v_cvt_u32_f32_e32 v4, v4
	v_mul_lo_u32 v1, v3, v4
	v_mul_hi_u32 v1, v4, v1
	v_add_u32_e32 v1, v4, v1
	v_mul_hi_u32 v1, v5, v1
	v_mul_lo_u32 v3, v1, v2
	v_sub_u32_e32 v3, v5, v3
	v_add_u32_e32 v4, 1, v1
	v_cmp_ge_u32_e32 vcc, v3, v2
	s_nop 1
	v_cndmask_b32_e32 v1, v1, v4, vcc
	v_sub_u32_e32 v4, v3, v2
	v_cndmask_b32_e32 v3, v3, v4, vcc
	v_add_u32_e32 v4, 1, v1
	v_cmp_ge_u32_e32 vcc, v3, v2
	v_add_u32_e32 v3, 1, v5
	s_nop 0
	v_cndmask_b32_e32 v1, v1, v4, vcc
	v_mul_lo_u32 v4, v2, v1
	v_add_u32_e32 v2, v4, v2
	v_cmp_ne_u32_e32 vcc, v3, v2
	s_and_saveexec_b64 s[8:9], vcc
	s_xor_b64 s[8:9], exec, s[8:9]
	s_cbranch_execz .LBB0_525
	s_waitcnt lgkmcnt(0)
	buffer_wbl2 sc1
	v_mov_b32_e32 v0, 0x2000
	global_load_dword v0, v0, s[6:7] offset:1024 sc1
	s_add_u32 s38, s6, 0x2400
	s_addc_u32 s39, s7, 0
	s_waitcnt vmcnt(0)
	v_cmp_eq_u32_e32 vcc, v0, v1
	s_and_saveexec_b64 s[10:11], vcc
	s_cbranch_execz .LBB0_524
	s_add_u32 s14, s22, 0x4200
	s_addc_u32 s15, s23, 0
	s_mov_b32 s3, 1
	s_mov_b64 s[42:43], 0
	v_mov_b32_e32 v0, 0
	s_branch .LBB0_515

.LBB0_596:
	s_or_b64 exec, exec, s[10:11]
	v_cvt_f32_u32_e32 v4, v2
	s_waitcnt vmcnt(0)
	v_readfirstlane_b32 s3, v3
	v_sub_u32_e32 v3, 0, v2
	v_rcp_iflag_f32_e32 v4, v4
	v_add_u32_e32 v5, s3, v1
	v_mul_f32_e32 v4, 0x4f7ffffe, v4
	v_cvt_u32_f32_e32 v4, v4
	v_mul_lo_u32 v1, v3, v4
	v_mul_hi_u32 v1, v4, v1
	v_add_u32_e32 v1, v4, v1
	v_mul_hi_u32 v1, v5, v1
	v_mul_lo_u32 v3, v1, v2
	v_sub_u32_e32 v3, v5, v3
	v_add_u32_e32 v4, 1, v1
	v_cmp_ge_u32_e32 vcc, v3, v2
	s_nop 1
	v_cndmask_b32_e32 v1, v1, v4, vcc
	v_sub_u32_e32 v4, v3, v2
	v_cndmask_b32_e32 v3, v3, v4, vcc
	v_add_u32_e32 v4, 1, v1
	v_cmp_ge_u32_e32 vcc, v3, v2
	v_add_u32_e32 v3, 1, v5
	s_nop 0
	v_cndmask_b32_e32 v1, v1, v4, vcc
	v_mul_lo_u32 v4, v2, v1
	v_add_u32_e32 v2, v4, v2
	v_cmp_ne_u32_e32 vcc, v3, v2
	s_and_saveexec_b64 s[8:9], vcc
	s_xor_b64 s[8:9], exec, s[8:9]
	s_cbranch_execz .LBB0_610
	s_waitcnt lgkmcnt(0)
	buffer_wbl2 sc1
	v_mov_b32_e32 v0, 0x2000
	global_load_dword v0, v0, s[6:7] offset:1024 sc1
	s_add_u32 s44, s6, 0x2400
	s_addc_u32 s45, s7, 0
	s_waitcnt vmcnt(0)
	v_cmp_eq_u32_e32 vcc, v0, v1
	s_and_saveexec_b64 s[10:11], vcc
	s_cbranch_execz .LBB0_609
	s_add_u32 s14, s22, 0x4200
	s_addc_u32 s15, s23, 0
	s_mov_b32 s3, 1
	s_mov_b64 s[46:47], 0
	v_mov_b32_e32 v0, 0
	s_branch .LBB0_600

.LBB0_680:
	s_or_b64 exec, exec, s[12:13]
	v_cvt_f32_u32_e32 v4, v2
	s_waitcnt vmcnt(0)
	v_readfirstlane_b32 s3, v3
	v_sub_u32_e32 v3, 0, v2
	v_rcp_iflag_f32_e32 v4, v4
	v_add_u32_e32 v5, s3, v1
	v_mul_f32_e32 v4, 0x4f7ffffe, v4
	v_cvt_u32_f32_e32 v4, v4
	v_mul_lo_u32 v1, v3, v4
	v_mul_hi_u32 v1, v4, v1
	v_add_u32_e32 v1, v4, v1
	v_mul_hi_u32 v1, v5, v1
	v_mul_lo_u32 v3, v1, v2
	v_sub_u32_e32 v3, v5, v3
	v_add_u32_e32 v4, 1, v1
	v_cmp_ge_u32_e32 vcc, v3, v2
	s_nop 1
	v_cndmask_b32_e32 v1, v1, v4, vcc
	v_sub_u32_e32 v4, v3, v2
	v_cndmask_b32_e32 v3, v3, v4, vcc
	v_add_u32_e32 v4, 1, v1
	v_cmp_ge_u32_e32 vcc, v3, v2
	v_add_u32_e32 v3, 1, v5
	s_nop 0
	v_cndmask_b32_e32 v1, v1, v4, vcc
	v_mul_lo_u32 v4, v2, v1
	v_add_u32_e32 v2, v4, v2
	v_cmp_ne_u32_e32 vcc, v3, v2
	s_and_saveexec_b64 s[10:11], vcc
	s_xor_b64 s[10:11], exec, s[10:11]
	s_cbranch_execz .LBB0_694
	s_waitcnt lgkmcnt(0)
	buffer_wbl2 sc1
	v_mov_b32_e32 v0, 0x2000
	global_load_dword v0, v0, s[8:9] offset:1024 sc1
	s_add_u32 s44, s8, 0x2400
	s_addc_u32 s45, s9, 0
	s_waitcnt vmcnt(0)
	v_cmp_eq_u32_e32 vcc, v0, v1
	s_and_saveexec_b64 s[12:13], vcc
	s_cbranch_execz .LBB0_693
	s_add_u32 s14, s22, 0x4200
	s_addc_u32 s15, s23, 0
	s_mov_b32 s3, 1
	s_mov_b64 s[46:47], 0
	v_mov_b32_e32 v0, 0
	s_branch .LBB0_684

.LBB0_1172:
	s_or_b64 exec, exec, s[12:13]
	v_cvt_f32_u32_e32 v4, v2
	s_waitcnt vmcnt(0)
	v_readfirstlane_b32 s3, v3
	v_sub_u32_e32 v3, 0, v2
	v_rcp_iflag_f32_e32 v4, v4
	v_add_u32_e32 v5, s3, v1
	v_mul_f32_e32 v4, 0x4f7ffffe, v4
	v_cvt_u32_f32_e32 v4, v4
	v_mul_lo_u32 v1, v3, v4
	v_mul_hi_u32 v1, v4, v1
	v_add_u32_e32 v1, v4, v1
	v_mul_hi_u32 v1, v5, v1
	v_mul_lo_u32 v3, v1, v2
	v_sub_u32_e32 v3, v5, v3
	v_add_u32_e32 v4, 1, v1
	v_cmp_ge_u32_e32 vcc, v3, v2
	s_nop 1
	v_cndmask_b32_e32 v1, v1, v4, vcc
	v_sub_u32_e32 v4, v3, v2
	v_cndmask_b32_e32 v3, v3, v4, vcc
	v_add_u32_e32 v4, 1, v1
	v_cmp_ge_u32_e32 vcc, v3, v2
	v_add_u32_e32 v3, 1, v5
	s_nop 0
	v_cndmask_b32_e32 v1, v1, v4, vcc
	v_mul_lo_u32 v4, v2, v1
	v_add_u32_e32 v2, v4, v2
	v_cmp_ne_u32_e32 vcc, v3, v2
	s_and_saveexec_b64 s[10:11], vcc
	s_xor_b64 s[10:11], exec, s[10:11]
	s_cbranch_execz .LBB0_1186
	s_waitcnt lgkmcnt(0)
	buffer_wbl2 sc1
	v_mov_b32_e32 v0, 0x2000
	global_load_dword v0, v0, s[8:9] offset:1024 sc1
	s_add_u32 s36, s8, 0x2400
	s_addc_u32 s37, s9, 0
	s_waitcnt vmcnt(0)
	v_cmp_eq_u32_e32 vcc, v0, v1
	s_and_saveexec_b64 s[12:13], vcc
	s_cbranch_execz .LBB0_1185
	s_add_u32 s14, s22, 0x4200
	s_addc_u32 s15, s23, 0
	s_mov_b32 s3, 1
	s_mov_b64 s[44:45], 0
	v_mov_b32_e32 v0, 0
	s_branch .LBB0_1176

.LBB0_1257:
	s_or_b64 exec, exec, s[10:11]
	v_cvt_f32_u32_e32 v4, v2
	s_waitcnt vmcnt(0)
	v_readfirstlane_b32 s8, v3
	v_sub_u32_e32 v3, 0, v2
	v_rcp_iflag_f32_e32 v4, v4
	v_add_u32_e32 v5, s8, v1
	v_mul_f32_e32 v4, 0x4f7ffffe, v4
	v_cvt_u32_f32_e32 v4, v4
	v_mul_lo_u32 v1, v3, v4
	v_mul_hi_u32 v1, v4, v1
	v_add_u32_e32 v1, v4, v1
	v_mul_hi_u32 v1, v5, v1
	v_mul_lo_u32 v3, v1, v2
	v_sub_u32_e32 v3, v5, v3
	v_add_u32_e32 v4, 1, v1
	v_cmp_ge_u32_e32 vcc, v3, v2
	s_nop 1
	v_cndmask_b32_e32 v1, v1, v4, vcc
	v_sub_u32_e32 v4, v3, v2
	v_cndmask_b32_e32 v3, v3, v4, vcc
	v_add_u32_e32 v4, 1, v1
	v_cmp_ge_u32_e32 vcc, v3, v2
	v_add_u32_e32 v3, 1, v5
	s_nop 0
	v_cndmask_b32_e32 v1, v1, v4, vcc
	v_mul_lo_u32 v4, v2, v1
	v_add_u32_e32 v2, v4, v2
	v_cmp_ne_u32_e32 vcc, v3, v2
	s_and_saveexec_b64 s[8:9], vcc
	s_xor_b64 s[8:9], exec, s[8:9]
	s_cbranch_execz .LBB0_1271
	s_waitcnt lgkmcnt(0)
	buffer_wbl2 sc1
	v_mov_b32_e32 v0, 0x2000
	global_load_dword v0, v0, s[6:7] offset:1024 sc1
	s_add_u32 s14, s6, 0x2400
	s_addc_u32 s15, s7, 0
	s_waitcnt vmcnt(0)
	v_cmp_eq_u32_e32 vcc, v0, v1
	s_and_saveexec_b64 s[10:11], vcc
	s_cbranch_execz .LBB0_1270
	s_add_u32 s12, s22, 0x4200
	s_addc_u32 s13, s23, 0
	s_mov_b32 s19, 1
	s_mov_b64 s[16:17], 0
	v_mov_b32_e32 v0, 0
	s_branch .LBB0_1261
